# slc loop software-pipelined per wave (5 LDS stages) + top-k rank loop bounded by qblk
# speedup vs baseline: 1.0116x; 1.0004x over previous
.LBB0_1298:
	v_readlane_b32 s18, v35, s24
	v_cmp_lt_u32_e64 s[20:21], s24, v0
	s_nop 0
	v_cmp_gt_f32_e64 s[16:17], s18, v35
	v_cmp_eq_f32_e64 s[18:19], s18, v35
	s_and_b64 s[18:19], s[18:19], s[20:21]
	s_or_b64 s[16:17], s[16:17], s[18:19]
	s_add_i32 s20, s24, 1
	v_addc_co_u32_e64 v36, s[16:17], 0, v36, s[16:17]
	v_readlane_b32 s18, v35, s20
	v_cmp_lt_u32_e64 s[20:21], s20, v0
	s_nop 0
	v_cmp_gt_f32_e64 s[16:17], s18, v35
	v_cmp_eq_f32_e64 s[18:19], s18, v35
	s_and_b64 s[18:19], s[18:19], s[20:21]
	s_add_i32 s20, s24, 2
	s_or_b64 s[16:17], s[16:17], s[18:19]
	v_readlane_b32 s18, v35, s20
	v_cndmask_b32_e64 v37, 0, 1, s[16:17]
	v_cmp_lt_u32_e64 s[20:21], s20, v0
	v_cmp_gt_f32_e64 s[16:17], s18, v35
	v_cmp_eq_f32_e64 s[18:19], s18, v35
	s_and_b64 s[18:19], s[18:19], s[20:21]
	s_or_b64 s[16:17], s[16:17], s[18:19]
	s_add_i32 s20, s24, 3
	v_addc_co_u32_e64 v36, s[16:17], v36, v37, s[16:17]
	v_readlane_b32 s18, v35, s20
	v_cmp_lt_u32_e64 s[20:21], s20, v0
	s_nop 0
	v_cmp_gt_f32_e64 s[16:17], s18, v35
	v_cmp_eq_f32_e64 s[18:19], s18, v35
	s_and_b64 s[18:19], s[18:19], s[20:21]
	s_add_i32 s20, s24, 4
	s_or_b64 s[16:17], s[16:17], s[18:19]
	v_readlane_b32 s18, v35, s20
	v_cndmask_b32_e64 v37, 0, 1, s[16:17]
	v_cmp_lt_u32_e64 s[20:21], s20, v0
	v_cmp_gt_f32_e64 s[16:17], s18, v35
	v_cmp_eq_f32_e64 s[18:19], s18, v35
	s_and_b64 s[18:19], s[18:19], s[20:21]
	s_or_b64 s[16:17], s[16:17], s[18:19]
	s_add_i32 s20, s24, 5
	v_addc_co_u32_e64 v36, s[16:17], v36, v37, s[16:17]
	v_readlane_b32 s18, v35, s20
	v_cmp_lt_u32_e64 s[20:21], s20, v0
	s_nop 0
	v_cmp_gt_f32_e64 s[16:17], s18, v35
	v_cmp_eq_f32_e64 s[18:19], s18, v35
	s_and_b64 s[18:19], s[18:19], s[20:21]
	s_add_i32 s20, s24, 6
	s_or_b64 s[16:17], s[16:17], s[18:19]
	v_readlane_b32 s18, v35, s20
	v_cndmask_b32_e64 v37, 0, 1, s[16:17]
	v_cmp_lt_u32_e64 s[20:21], s20, v0
	v_cmp_gt_f32_e64 s[16:17], s18, v35
	v_cmp_eq_f32_e64 s[18:19], s18, v35
	s_and_b64 s[18:19], s[18:19], s[20:21]
	s_add_i32 s20, s24, 7
	s_or_b64 s[16:17], s[16:17], s[18:19]
	v_readlane_b32 s18, v35, s20
	v_add_u32_e32 v36, v36, v37
	v_cndmask_b32_e64 v37, 0, 1, s[16:17]
	v_cmp_gt_f32_e64 s[16:17], s18, v35
	v_cmp_eq_f32_e64 s[18:19], s18, v35
	v_cmp_lt_u32_e64 s[20:21], s20, v0
	s_and_b64 s[18:19], s[18:19], s[20:21]
	s_or_b64 s[16:17], s[16:17], s[18:19]
	s_add_i32 s24, s24, 8
	v_addc_co_u32_e64 v36, s[16:17], v36, v37, s[16:17]
	s_cmp_gt_u32 s24, s27
	s_cbranch_scc0 .LBB0_1298
	v_cmp_gt_u32_e64 s[16:17], 16, v36
	s_and_b64 s[16:17], s[16:17], s[14:15]
	s_nop 0
	v_cndmask_b32_e64 v35, 0, 1, s[16:17]
	v_cmp_ne_u32_e64 s[16:17], 0, v35
	s_and_saveexec_b64 s[18:19], vcc
	s_cbranch_execz .LBB0_1296
	s_lshl_b32 s7, s7, 3
	s_add_i32 s7, s7, 0
	s_add_i32 s7, s7, 0x10800
	v_mov_b32_e32 v35, s7
	v_mov_b64_e32 v[36:37], s[16:17]
	ds_write_b64 v35, v[36:37]
	s_branch .LBB0_1296

.LBB0_1327:
	v_and_b32_e32 v38, 63, v36
	v_lshrrev_b32_e32 v39, 5, v38
	v_lshrrev_b32_e32 v40, 1, v36
	v_bitop3_b32 v39, v40, v39, 1 bitop3:0x6c
	v_lshlrev_b32_e32 v111, 4, v39
	v_bfe_u32 v39, v36, 2, 2
	v_lshl_add_u64 v[100:101], v[0:1], 1, s[12:13]
	v_lshrrev_b32_e32 v0, 3, v36
	v_and_b32_e32 v116, 4, v0
	v_and_or_b32 v0, v37, 4, v39
	v_lshlrev_b32_e32 v117, 7, v0
	v_lshlrev_b32_e32 v0, 1, v38
	s_cmp_lt_i32 s18, 0
	s_cbranch_scc1 .Lslc_pw0
	s_waitcnt vmcnt(2)
	s_branch .Lslc_pw1

.Lslc_pw1:
	s_add_u32 s16, s10, -1
	s_waitcnt lgkmcnt(0)
	s_barrier
	v_and_b32_e32 v118, 32, v0
	v_lshlrev_b32_e32 v0, 3, v38
	s_addc_u32 s17, s11, -1
	v_lshlrev_b32_e32 v41, 7, v38
	v_lshlrev_b32_e32 v112, 5, v39
	v_and_b32_e32 v119, 16, v0
	v_and_b32_e32 v120, 8, v0
	v_lshlrev_b32_e32 v0, 6, v37
	v_mov_b32_e32 v123, 0
	s_and_b64 s[10:11], s[16:17], s[10:11]
	v_and_b32_e32 v110, 0xf80, v41
	v_xor_b32_e32 v113, 32, v112
	v_xor_b32_e32 v114, 64, v112
	v_xor_b32_e32 v115, 0x60, v112
	s_sub_i32 s54, s26, 63
	v_lshl_add_u64 v[102:103], v[34:35], 1, s[14:15]
	v_and_b32_e32 v121, 64, v0
	v_bitop3_b32 v122, v0, 64, v0 bitop3:0xc
	s_mov_b32 s14, 0
	v_mov_b32_e32 v124, 0xf149f2ca
	v_mov_b32_e32 v34, 0
	v_mov_b32_e32 v35, v123
	v_mov_b32_e32 v36, v123
	v_mov_b32_e32 v37, v123
	v_mov_b32_e32 v38, v123
	v_mov_b32_e32 v39, v123
	v_mov_b32_e32 v40, v123
	v_mov_b32_e32 v41, v123
	v_mov_b32_e32 v42, v123
	v_mov_b32_e32 v43, v123
	v_mov_b32_e32 v44, v123
	v_mov_b32_e32 v45, v123
	v_mov_b32_e32 v46, v123
	v_mov_b32_e32 v47, v123
	v_mov_b32_e32 v48, v123
	v_mov_b32_e32 v49, v123
	v_mov_b32_e32 v50, 0
	v_mov_b32_e32 v51, v123
	v_mov_b32_e32 v52, v123
	v_mov_b32_e32 v53, v123
	v_mov_b32_e32 v54, v123
	v_mov_b32_e32 v55, v123
	v_mov_b32_e32 v56, v123
	v_mov_b32_e32 v57, v123
	v_mov_b32_e32 v58, v123
	v_mov_b32_e32 v59, v123
	v_mov_b32_e32 v60, v123
	v_mov_b32_e32 v61, v123
	v_mov_b32_e32 v62, v123
	v_mov_b32_e32 v63, v123
	v_mov_b32_e32 v64, v123
	v_mov_b32_e32 v65, v123
	s_mov_b32 s78, 0
	s_mov_b32 s79, 0
	v_mov_b32_e32 v224, 0
	v_mov_b32_e32 v225, 0
	v_mov_b32_e32 v226, 0
	v_mov_b32_e32 v227, 0
	v_mov_b32_e32 v228, 0
	v_mov_b32_e32 v229, 0
	v_mov_b32_e32 v230, 0
	v_mov_b32_e32 v231, 0
	v_mov_b32_e32 v232, 0
	v_mov_b32_e32 v233, 0
	v_mov_b32_e32 v234, 0
	v_mov_b32_e32 v235, 0
	v_mov_b32_e32 v236, 0
	v_mov_b32_e32 v237, 0
	v_mov_b32_e32 v238, 0
	v_mov_b32_e32 v239, 0
	v_add3_u32 v125, s79, v110, v111
	v_add_u32_e32 v174, v125, v112
	v_add_u32_e32 v175, v125, v113
	v_add_u32_e32 v252, v125, v114
	v_add_u32_e32 v253, v125, v115
	ds_read_b128 v[158:161], v174
	ds_read_b128 v[162:165], v175
	ds_read_b128 v[166:169], v252
	ds_read_b128 v[170:173], v253
	ds_read_b128 v[240:243], v174 offset:4096
	ds_read_b128 v[244:247], v175 offset:4096
	ds_read_b128 v[248:251], v252 offset:4096
	ds_read_b128 v[104:107], v253 offset:4096
	s_waitcnt lgkmcnt(7)
	v_mfma_f32_32x32x16_bf16 v[66:81], v[158:161], v[130:133], 0
	s_waitcnt lgkmcnt(6)
	v_mfma_f32_32x32x16_bf16 v[66:81], v[162:165], v[134:137], v[66:81]
	s_waitcnt lgkmcnt(5)
	v_mfma_f32_32x32x16_bf16 v[66:81], v[166:169], v[138:141], v[66:81]
	s_waitcnt lgkmcnt(4)
	v_mfma_f32_32x32x16_bf16 v[66:81], v[170:173], v[142:145], v[66:81]
	s_waitcnt lgkmcnt(3)
	v_mfma_f32_32x32x16_bf16 v[82:97], v[240:243], v[130:133], 0
	s_waitcnt lgkmcnt(2)
	v_mfma_f32_32x32x16_bf16 v[82:97], v[244:247], v[134:137], v[82:97]
	s_waitcnt lgkmcnt(1)
	v_mfma_f32_32x32x16_bf16 v[82:97], v[248:251], v[138:141], v[82:97]
	s_waitcnt lgkmcnt(0)
	v_mfma_f32_32x32x16_bf16 v[82:97], v[104:107], v[142:145], v[82:97]
.LBB0_1328:
	s_ff1_i32_b64 s96, s[10:11]
	s_cmp_lg_u64 s[10:11], 0
	s_cselect_b32 s96, s96, -1
	s_cmp_lt_i32 s96, 0
	s_cbranch_scc1 .Lslc_nodma
	s_add_i32 s13, s14, 3
	s_cmp_ge_u32 s13, 5
	s_cselect_b32 s16, 5, 0
	s_sub_i32 s13, s13, s16
	s_lshl_b32 s16, s13, 14
	s_cmp_eq_u32 s13, 4
	s_cselect_b32 s13, 0xa40, 0
	s_add_i32 s13, s13, s16
	s_lshl_b32 s16, s96, 6
	s_mul_i32 s17, s83, s16
	s_mul_hi_u32 s19, s82, s16
	s_add_i32 s17, s19, s17
	s_mul_i32 s16, s82, s16
	s_add_i32 s13, s13, 0
	s_lshl_b64 s[16:17], s[16:17], 1
	v_lshl_add_u64 v[106:107], v[100:101], 0, s[16:17]
	s_add_i32 s13, s92, s13
	s_mov_b32 s19, m0
	s_mov_b32 m0, s13
	s_nop 0
	global_load_lds_dwordx4 v[106:107], off
	s_mov_b32 m0, s19
	v_lshl_add_u64 v[106:107], v[102:103], 0, s[16:17]
	s_addk_i32 s13, 0x2000
	s_mov_b32 s16, m0
	s_mov_b32 m0, s13
	s_nop 0
	global_load_lds_dwordx4 v[106:107], off
	s_mov_b32 m0, s16
.Lslc_nodma:
	s_lshl_b32 s15, s6, 6
	s_sub_i32 s16, s54, s15
	s_cmpk_gt_i32 s16, 0x70
	s_cbranch_scc1 .LBB0_1330
	v_or_b32_e32 v0, s15, v116
	v_sub_u32_e32 v0, v156, v0
	v_add_u32_e32 v125, -1, v0
	v_subrev_u32_e32 v191, 33, v0
	v_subrev_u32_e32 v194, 32, v0
	v_subrev_u32_e32 v198, 34, v0
	v_med3_i32 v104, v0, 0, v181
	v_med3_i32 v105, v125, 0, v181
	v_med3_i32 v106, v194, 0, v181
	v_med3_i32 v107, v191, 0, v181
	v_add_u32_e32 v195, -3, v0
	v_add_u32_e32 v196, -2, v0
	v_subrev_u32_e32 v197, 35, v0
	v_med3_i32 v126, v198, 0, v181
	v_lshl_add_u32 v104, v104, 2, s5
	v_lshl_add_u32 v105, v105, 2, s5
	v_lshl_add_u32 v106, v106, 2, s5
	v_lshl_add_u32 v107, v107, 2, s5
	v_med3_i32 v108, v196, 0, v181
	v_med3_i32 v109, v195, 0, v181
	v_lshl_add_u32 v158, v126, 2, s5
	v_med3_i32 v126, v197, 0, v181
	v_lshl_add_u32 v108, v108, 2, s5
	v_lshl_add_u32 v109, v109, 2, s5
	v_lshl_add_u32 v159, v126, 2, s5
	ds_read_b32 v126, v104
	ds_read_b32 v127, v105
	ds_read_b32 v106, v106
	ds_read_b32 v107, v107
	ds_read_b32 v128, v108
	ds_read_b32 v129, v109
	ds_read_b32 v104, v158
	ds_read_b32 v105, v159
	v_subrev_u32_e32 v202, 40, v0
	v_subrev_u32_e32 v201, 41, v0
	v_med3_i32 v158, v202, 0, v181
	v_lshl_add_u32 v160, v158, 2, s5
	v_med3_i32 v158, v201, 0, v181
	v_add_u32_e32 v204, -10, v0
	v_lshl_add_u32 v161, v158, 2, s5
	v_add_u32_e32 v203, -11, v0
	v_med3_i32 v158, v204, 0, v181
	v_add_u32_e32 v199, -9, v0
	v_add_u32_e32 v200, -8, v0
	v_lshl_add_u32 v162, v158, 2, s5
	v_med3_i32 v158, v203, 0, v181
	v_subrev_u32_e32 v206, 42, v0
	v_med3_i32 v108, v200, 0, v181
	v_med3_i32 v109, v199, 0, v181
	v_lshl_add_u32 v163, v158, 2, s5
	v_subrev_u32_e32 v205, 43, v0
	v_med3_i32 v158, v206, 0, v181
	v_lshl_add_u32 v108, v108, 2, s5
	v_lshl_add_u32 v109, v109, 2, s5
	v_lshl_add_u32 v164, v158, 2, s5
	v_med3_i32 v158, v205, 0, v181
	v_lshl_add_u32 v165, v158, 2, s5
	ds_read_b32 v158, v108
	ds_read_b32 v159, v109
	ds_read_b32 v160, v160
	ds_read_b32 v161, v161
	ds_read_b32 v162, v162
	ds_read_b32 v163, v163
	ds_read_b32 v108, v164
	ds_read_b32 v109, v165
	v_subrev_u32_e32 v207, 17, v0
	v_add_u32_e32 v208, -16, v0
	v_subrev_u32_e32 v209, 49, v0
	v_subrev_u32_e32 v210, 48, v0
	v_subrev_u32_e32 v211, 19, v0
	v_subrev_u32_e32 v212, 18, v0
	v_subrev_u32_e32 v213, 51, v0
	v_subrev_u32_e32 v214, 50, v0
	v_med3_i32 v164, v208, 0, v181
	v_med3_i32 v165, v207, 0, v181
	v_med3_i32 v166, v210, 0, v181
	v_med3_i32 v167, v209, 0, v181
	v_med3_i32 v168, v212, 0, v181
	v_med3_i32 v169, v211, 0, v181
	v_med3_i32 v170, v214, 0, v181
	v_med3_i32 v171, v213, 0, v181
	v_lshl_add_u32 v164, v164, 2, s5
	v_lshl_add_u32 v165, v165, 2, s5
	v_lshl_add_u32 v166, v166, 2, s5
	v_lshl_add_u32 v167, v167, 2, s5
	v_lshl_add_u32 v168, v168, 2, s5
	v_lshl_add_u32 v169, v169, 2, s5
	v_lshl_add_u32 v170, v170, 2, s5
	v_lshl_add_u32 v171, v171, 2, s5
	ds_read_b32 v164, v164
	ds_read_b32 v165, v165
	ds_read_b32 v166, v166
	ds_read_b32 v167, v167
	ds_read_b32 v168, v168
	ds_read_b32 v169, v169
	ds_read_b32 v170, v170
	ds_read_b32 v171, v171
	s_waitcnt lgkmcnt(14)
	v_pk_add_f32 v[68:69], v[68:69], v[128:129]
	v_cmp_gt_u32_e32 vcc, 2.0, v195
	v_pk_add_f32 v[66:67], v[66:67], v[126:127]
	s_waitcnt lgkmcnt(10)
	v_pk_add_f32 v[72:73], v[72:73], v[162:163]
	v_cndmask_b32_e32 v69, v182, v69, vcc
	v_cmp_gt_u32_e32 vcc, 2.0, v196
	v_pk_add_f32 v[70:71], v[70:71], v[158:159]
	v_subrev_u32_e32 v215, 25, v0
	v_cndmask_b32_e32 v68, v182, v68, vcc
	v_cmp_gt_u32_e32 vcc, 2.0, v125
	v_subrev_u32_e32 v216, 24, v0
	v_subrev_u32_e32 v217, 57, v0
	v_cndmask_b32_e32 v67, v182, v67, vcc
	v_cmp_gt_u32_e32 vcc, 2.0, v0
	v_subrev_u32_e32 v218, 56, v0
	v_subrev_u32_e32 v219, 27, v0
	v_cndmask_b32_e32 v66, v182, v66, vcc
	v_cmp_gt_u32_e32 vcc, 2.0, v203
	v_subrev_u32_e32 v220, 26, v0
	v_subrev_u32_e32 v221, 59, v0
	v_cndmask_b32_e32 v73, v182, v73, vcc
	v_cmp_gt_u32_e32 vcc, 2.0, v204
	v_subrev_u32_e32 v222, 58, v0
	v_med3_i32 v172, v216, 0, v181
	v_cndmask_b32_e32 v72, v182, v72, vcc
	v_cmp_gt_u32_e32 vcc, 2.0, v199
	v_med3_i32 v173, v215, 0, v181
	v_med3_i32 v174, v218, 0, v181
	v_cndmask_b32_e32 v71, v182, v71, vcc
	v_cmp_gt_u32_e32 vcc, 2.0, v200
	v_med3_i32 v175, v217, 0, v181
	v_med3_i32 v178, v220, 0, v181
	v_med3_i32 v179, v219, 0, v181
	v_med3_i32 v192, v222, 0, v181
	v_med3_i32 v193, v221, 0, v181
	s_waitcnt lgkmcnt(2)
	v_pk_add_f32 v[76:77], v[76:77], v[168:169]
	v_cndmask_b32_e32 v70, v182, v70, vcc
	v_cmp_gt_u32_e32 vcc, 2.0, v211
	v_lshl_add_u32 v172, v172, 2, s5
	v_lshl_add_u32 v173, v173, 2, s5
	v_lshl_add_u32 v174, v174, 2, s5
	v_lshl_add_u32 v175, v175, 2, s5
	v_lshl_add_u32 v178, v178, 2, s5
	v_lshl_add_u32 v179, v179, 2, s5
	v_lshl_add_u32 v192, v192, 2, s5
	v_lshl_add_u32 v193, v193, 2, s5
	v_cndmask_b32_e32 v77, v182, v77, vcc
	v_cmp_gt_u32_e32 vcc, 2.0, v212
	ds_read_b32 v172, v172
	ds_read_b32 v173, v173
	ds_read_b32 v174, v174
	ds_read_b32 v178, v178
	ds_read_b32 v179, v179
	ds_read_b32 v192, v192
	ds_read_b32 v193, v193
	ds_read_b32 v175, v175
	v_pk_add_f32 v[74:75], v[74:75], v[164:165]
	v_cndmask_b32_e32 v76, v182, v76, vcc
	v_cmp_gt_u32_e32 vcc, 2.0, v207
	s_waitcnt lgkmcnt(3)
	v_pk_add_f32 v[80:81], v[80:81], v[178:179]
	v_pk_add_f32 v[78:79], v[78:79], v[172:173]
	v_cndmask_b32_e32 v75, v182, v75, vcc
	v_cmp_gt_u32_e32 vcc, 2.0, v208
	v_pk_add_f32 v[84:85], v[84:85], v[104:105]
	v_pk_add_f32 v[82:83], v[82:83], v[106:107]
	v_cndmask_b32_e32 v74, v182, v74, vcc
	v_cmp_gt_u32_e32 vcc, 2.0, v219
	v_pk_add_f32 v[88:89], v[88:89], v[108:109]
	v_pk_add_f32 v[86:87], v[86:87], v[160:161]
	v_cndmask_b32_e32 v81, v182, v81, vcc
	v_cmp_gt_u32_e32 vcc, 2.0, v220
	v_pk_add_f32 v[92:93], v[92:93], v[170:171]
	v_pk_add_f32 v[90:91], v[90:91], v[166:167]
	v_cndmask_b32_e32 v80, v182, v80, vcc
	v_cmp_gt_u32_e32 vcc, 2.0, v215
	s_waitcnt lgkmcnt(1)
	v_pk_add_f32 v[96:97], v[96:97], v[192:193]
	s_waitcnt lgkmcnt(0)
	v_pk_add_f32 v[94:95], v[94:95], v[174:175]
	v_cndmask_b32_e32 v79, v182, v79, vcc
	v_cmp_gt_u32_e32 vcc, 2.0, v216
	s_nop 1
	v_cndmask_b32_e32 v78, v182, v78, vcc
	v_cmp_gt_u32_e32 vcc, 2.0, v197
	s_nop 1
	v_cndmask_b32_e32 v85, v182, v85, vcc
	v_cmp_gt_u32_e32 vcc, 2.0, v198
	s_nop 1
	v_cndmask_b32_e32 v84, v182, v84, vcc
	v_cmp_gt_u32_e32 vcc, 2.0, v191
	s_nop 1
	v_cndmask_b32_e32 v83, v182, v83, vcc
	v_cmp_gt_u32_e32 vcc, 2.0, v194
	s_nop 1
	v_cndmask_b32_e32 v82, v182, v82, vcc
	v_cmp_gt_u32_e32 vcc, 2.0, v205
	s_nop 1
	v_cndmask_b32_e32 v89, v182, v89, vcc
	v_cmp_gt_u32_e32 vcc, 2.0, v206
	s_nop 1
	v_cndmask_b32_e32 v88, v182, v88, vcc
	v_cmp_gt_u32_e32 vcc, 2.0, v201
	s_nop 1
	v_cndmask_b32_e32 v87, v182, v87, vcc
	v_cmp_gt_u32_e32 vcc, 2.0, v202
	s_nop 1
	v_cndmask_b32_e32 v86, v182, v86, vcc
	v_cmp_gt_u32_e32 vcc, 2.0, v213
	s_nop 1
	v_cndmask_b32_e32 v93, v182, v93, vcc
	v_cmp_gt_u32_e32 vcc, 2.0, v214
	s_nop 1
	v_cndmask_b32_e32 v92, v182, v92, vcc
	v_cmp_gt_u32_e32 vcc, 2.0, v209
	s_nop 1
	v_cndmask_b32_e32 v91, v182, v91, vcc
	v_cmp_gt_u32_e32 vcc, 2.0, v210
	s_nop 1
	v_cndmask_b32_e32 v90, v182, v90, vcc
	v_cmp_gt_u32_e32 vcc, 2.0, v221
	s_nop 1
	v_cndmask_b32_e32 v97, v182, v97, vcc
	v_cmp_gt_u32_e32 vcc, 2.0, v222
	s_nop 1
	v_cndmask_b32_e32 v96, v182, v96, vcc
	v_cmp_gt_u32_e32 vcc, 2.0, v217
	s_nop 1
	v_cndmask_b32_e32 v95, v182, v95, vcc
	v_cmp_gt_u32_e32 vcc, 2.0, v218
	s_nop 1
	v_cndmask_b32_e32 v94, v182, v94, vcc
.LBB0_1330:
	v_add3_u32 v0, s78, v117, v118
	v_add3_u32 v0, v0, v119, v120
	v_add_u32_e32 v252, v0, v121
	v_add_u32_e32 v253, v0, v122
	ds_read_b64_tr_b16 v[192:193], v252 offset:8192
	ds_read_b64_tr_b16 v[194:195], v252 offset:9216
	ds_read_b64_tr_b16 v[196:197], v253 offset:8192
	ds_read_b64_tr_b16 v[198:199], v253 offset:9216
	ds_read_b64_tr_b16 v[200:201], v252 offset:10240
	ds_read_b64_tr_b16 v[202:203], v252 offset:11264
	ds_read_b64_tr_b16 v[204:205], v253 offset:10240
	ds_read_b64_tr_b16 v[206:207], v253 offset:11264
	ds_read_b64_tr_b16 v[208:209], v252 offset:12288
	ds_read_b64_tr_b16 v[210:211], v252 offset:13312
	ds_read_b64_tr_b16 v[212:213], v253 offset:12288
	ds_read_b64_tr_b16 v[214:215], v253 offset:13312
	v_max3_f32 v0, v66, v67, v68
	v_max3_f32 v125, v69, v70, v71
	v_max3_f32 v126, v72, v73, v74
	v_max3_f32 v127, v75, v76, v77
	v_max3_f32 v0, v0, v78, v79
	v_max3_f32 v125, v125, v80, v81
	v_max3_f32 v126, v126, v82, v83
	v_max3_f32 v127, v127, v84, v85
	v_max3_f32 v0, v0, v86, v87
	v_max3_f32 v125, v125, v88, v89
	v_max3_f32 v126, v126, v90, v91
	v_max3_f32 v127, v127, v92, v93
	v_max3_f32 v0, v0, v94, v95
	v_max3_f32 v125, v125, v96, v97
	v_max3_f32 v0, v0, v125, v126
	v_max_f32_e32 v125, v0, v127
	v_mov_b32_e32 v126, v125
	s_waitcnt lgkmcnt(8)
	v_mfma_f32_32x32x16_bf16 v[50:65], v[192:195], v[224:227], v[50:65]
	v_mfma_f32_32x32x16_bf16 v[34:49], v[196:199], v[224:227], v[34:49]
	ds_read_b64_tr_b16 v[216:217], v252 offset:14336
	ds_read_b64_tr_b16 v[218:219], v252 offset:15360
	ds_read_b64_tr_b16 v[220:221], v253 offset:14336
	ds_read_b64_tr_b16 v[222:223], v253 offset:15360
	v_permlane32_swap_b32 v125, v126
	v_lshrrev_b64 v[128:129], s6, v[98:99]
	v_and_b32_e32 v0, 1, v128
	v_max_f32_e32 v125, v125, v126
	v_cmp_eq_u64_e64 s[16:17], 0, v[0:1]
	s_nop 1
	v_cndmask_b32_e64 v126, v125, v182, s[16:17]
	v_sub_f32_e32 v0, v126, v124
	v_cmp_lt_f32_e32 vcc, 0x41000000, v0
	s_cbranch_vccnz .Lslc_rare
	v_cndmask_b32_e64 v129, v124, v180, s[16:17]
	v_sub_f32_e32 v0, v66, v129
	v_sub_f32_e32 v126, v67, v129
	v_sub_f32_e32 v127, v68, v129
	v_sub_f32_e32 v128, v69, v129
	v_exp_f32_e32 v66, v0
	v_exp_f32_e32 v67, v126
	v_exp_f32_e32 v68, v127
	v_exp_f32_e32 v69, v128
	s_waitcnt lgkmcnt(8)
	v_mfma_f32_32x32x16_bf16 v[50:65], v[200:203], v[228:231], v[50:65]
	v_mfma_f32_32x32x16_bf16 v[34:49], v[204:207], v[228:231], v[34:49]
	v_sub_f32_e32 v0, v70, v129
	v_sub_f32_e32 v126, v71, v129
	v_sub_f32_e32 v127, v72, v129
	v_sub_f32_e32 v128, v73, v129
	v_exp_f32_e32 v70, v0
	v_exp_f32_e32 v71, v126
	v_exp_f32_e32 v72, v127
	v_exp_f32_e32 v73, v128
	s_waitcnt lgkmcnt(4)
	v_mfma_f32_32x32x16_bf16 v[50:65], v[208:211], v[232:235], v[50:65]
	v_mfma_f32_32x32x16_bf16 v[34:49], v[212:215], v[232:235], v[34:49]
	s_add_i32 s12, s14, 1
	s_cmp_ge_u32 s12, 5
	s_cselect_b32 s13, 5, 0
	s_sub_i32 s12, s12, s13
	s_lshl_b32 s13, s12, 14
	s_cmp_eq_u32 s12, 4
	s_cselect_b32 s12, 0xa40, 0
	s_add_i32 s12, s12, s13
	s_cmp_lt_i32 s7, 0
	s_cselect_b32 s12, s79, s12
	v_add3_u32 v125, s12, v110, v111
	v_add_u32_e32 v174, v125, v112
	v_add_u32_e32 v175, v125, v113
	v_add_u32_e32 v252, v125, v114
	v_add_u32_e32 v253, v125, v115
	ds_read_b128 v[158:161], v174
	ds_read_b128 v[162:165], v175
	ds_read_b128 v[166:169], v252
	ds_read_b128 v[170:173], v253
	ds_read_b128 v[240:243], v174 offset:4096
	ds_read_b128 v[244:247], v175 offset:4096
	ds_read_b128 v[248:251], v252 offset:4096
	ds_read_b128 v[104:107], v253 offset:4096
	v_sub_f32_e32 v0, v74, v129
	v_sub_f32_e32 v126, v75, v129
	v_sub_f32_e32 v127, v76, v129
	v_sub_f32_e32 v128, v77, v129
	v_exp_f32_e32 v74, v0
	v_exp_f32_e32 v75, v126
	v_exp_f32_e32 v76, v127
	v_exp_f32_e32 v77, v128
	s_waitcnt lgkmcnt(8)
	v_mfma_f32_32x32x16_bf16 v[50:65], v[216:219], v[236:239], v[50:65]
	v_mfma_f32_32x32x16_bf16 v[34:49], v[220:223], v[236:239], v[34:49]
	v_sub_f32_e32 v0, v78, v129
	v_sub_f32_e32 v126, v79, v129
	v_sub_f32_e32 v127, v80, v129
	v_sub_f32_e32 v128, v81, v129
	v_exp_f32_e32 v78, v0
	v_exp_f32_e32 v79, v126
	v_exp_f32_e32 v80, v127
	v_exp_f32_e32 v81, v128
.Lslc_s0done:
	v_cvt_pk_bf16_f32 v224, v66, v67
	v_cvt_pk_bf16_f32 v225, v68, v69
	v_cvt_pk_bf16_f32 v226, v70, v71
	v_cvt_pk_bf16_f32 v227, v72, v73
	v_cvt_pk_bf16_f32 v228, v74, v75
	v_cvt_pk_bf16_f32 v229, v76, v77
	v_cvt_pk_bf16_f32 v230, v78, v79
	v_cvt_pk_bf16_f32 v231, v80, v81
	v_add_f32_e32 v108, v66, v70
	v_add_f32_e32 v109, v67, v71
	v_add_f32_e32 v178, v68, v72
	v_add_f32_e32 v179, v69, v73
	v_add_f32_e32 v108, v108, v74
	v_add_f32_e32 v109, v109, v75
	v_add_f32_e32 v178, v178, v76
	v_add_f32_e32 v179, v179, v77
	v_add_f32_e32 v108, v108, v78
	v_add_f32_e32 v109, v109, v79
	v_add_f32_e32 v178, v178, v80
	v_add_f32_e32 v179, v179, v81
	s_waitcnt lgkmcnt(4)
	v_mfma_f32_32x32x16_bf16 v[66:81], v[158:161], v[130:133], 0
	v_sub_f32_e32 v0, v82, v129
	v_sub_f32_e32 v126, v83, v129
	v_sub_f32_e32 v127, v84, v129
	v_sub_f32_e32 v128, v85, v129
	v_exp_f32_e32 v82, v0
	v_exp_f32_e32 v83, v126
	v_exp_f32_e32 v84, v127
	v_exp_f32_e32 v85, v128
	v_mfma_f32_32x32x16_bf16 v[66:81], v[162:165], v[134:137], v[66:81]
	v_sub_f32_e32 v0, v86, v129
	v_sub_f32_e32 v126, v87, v129
	v_sub_f32_e32 v127, v88, v129
	v_sub_f32_e32 v128, v89, v129
	v_exp_f32_e32 v86, v0
	v_exp_f32_e32 v87, v126
	v_exp_f32_e32 v88, v127
	v_exp_f32_e32 v89, v128
	v_mfma_f32_32x32x16_bf16 v[66:81], v[166:169], v[138:141], v[66:81]
	v_sub_f32_e32 v0, v90, v129
	v_sub_f32_e32 v126, v91, v129
	v_sub_f32_e32 v127, v92, v129
	v_sub_f32_e32 v128, v93, v129
	v_exp_f32_e32 v90, v0
	v_exp_f32_e32 v91, v126
	v_exp_f32_e32 v92, v127
	v_exp_f32_e32 v93, v128
	v_mfma_f32_32x32x16_bf16 v[66:81], v[170:173], v[142:145], v[66:81]
	v_sub_f32_e32 v0, v94, v129
	v_sub_f32_e32 v126, v95, v129
	v_sub_f32_e32 v127, v96, v129
	v_sub_f32_e32 v128, v97, v129
	v_exp_f32_e32 v94, v0
	v_exp_f32_e32 v95, v126
	v_exp_f32_e32 v96, v127
	v_exp_f32_e32 v97, v128
	v_cvt_pk_bf16_f32 v232, v82, v83
	v_cvt_pk_bf16_f32 v233, v84, v85
	v_cvt_pk_bf16_f32 v234, v86, v87
	v_cvt_pk_bf16_f32 v235, v88, v89
	v_cvt_pk_bf16_f32 v236, v90, v91
	v_cvt_pk_bf16_f32 v237, v92, v93
	v_cvt_pk_bf16_f32 v238, v94, v95
	v_cvt_pk_bf16_f32 v239, v96, v97
	v_add_f32_e32 v108, v108, v82
	v_add_f32_e32 v109, v109, v83
	v_add_f32_e32 v178, v178, v84
	v_add_f32_e32 v179, v179, v85
	v_add_f32_e32 v108, v108, v86
	v_add_f32_e32 v109, v109, v87
	v_add_f32_e32 v178, v178, v88
	v_add_f32_e32 v179, v179, v89
	v_add_f32_e32 v108, v108, v90
	v_add_f32_e32 v109, v109, v91
	v_add_f32_e32 v178, v178, v92
	v_add_f32_e32 v179, v179, v93
	v_add_f32_e32 v108, v108, v94
	v_add_f32_e32 v109, v109, v95
	v_add_f32_e32 v178, v178, v96
	v_add_f32_e32 v179, v179, v97
	s_waitcnt lgkmcnt(0)
	v_mfma_f32_32x32x16_bf16 v[82:97], v[240:243], v[130:133], 0
	v_mfma_f32_32x32x16_bf16 v[82:97], v[244:247], v[134:137], v[82:97]
	v_mfma_f32_32x32x16_bf16 v[82:97], v[248:251], v[138:141], v[82:97]
	v_mfma_f32_32x32x16_bf16 v[82:97], v[104:107], v[142:145], v[82:97]
	v_add_f32_e32 v108, v108, v109
	v_add_f32_e32 v178, v178, v179
	v_add_f32_e32 v108, v108, v178
	v_add_f32_e32 v123, v123, v108
	s_cmp_lt_i32 s96, 0
	s_cbranch_scc1 .Lslc_w0
	s_waitcnt vmcnt(2)
	s_branch .Lslc_w1

.Lslc_w1:
	s_waitcnt lgkmcnt(0)
	s_barrier
	s_add_u32 s16, s10, -1
	s_addc_u32 s17, s11, -1
	s_and_b64 s[10:11], s[16:17], s[10:11]
	s_mov_b32 s78, s79
	s_cmp_lt_i32 s7, 0
	s_cbranch_scc1 .Lslc_done
	s_mov_b32 s6, s7
	s_mov_b32 s7, s18
	s_mov_b32 s18, s96
	s_add_i32 s14, s14, 1
	s_cmp_ge_u32 s14, 5
	s_cselect_b32 s16, 5, 0
	s_sub_i32 s14, s14, s16
	s_lshl_b32 s16, s14, 14
	s_cmp_eq_u32 s14, 4
	s_cselect_b32 s79, 0xa40, 0
	s_add_i32 s79, s79, s16
	s_branch .LBB0_1328
.Lslc_rare:
	s_waitcnt lgkmcnt(8)
	v_mfma_f32_32x32x16_bf16 v[50:65], v[200:203], v[228:231], v[50:65]
	v_mfma_f32_32x32x16_bf16 v[34:49], v[204:207], v[228:231], v[34:49]
	s_waitcnt lgkmcnt(4)
	v_mfma_f32_32x32x16_bf16 v[50:65], v[208:211], v[232:235], v[50:65]
	v_mfma_f32_32x32x16_bf16 v[34:49], v[212:215], v[232:235], v[34:49]
	s_waitcnt lgkmcnt(0)
	v_mfma_f32_32x32x16_bf16 v[50:65], v[216:219], v[236:239], v[50:65]
	v_mfma_f32_32x32x16_bf16 v[34:49], v[220:223], v[236:239], v[34:49]
	s_add_i32 s12, s14, 1
	s_cmp_ge_u32 s12, 5
	s_cselect_b32 s13, 5, 0
	s_sub_i32 s12, s12, s13
	s_lshl_b32 s13, s12, 14
	s_cmp_eq_u32 s12, 4
	s_cselect_b32 s12, 0xa40, 0
	s_add_i32 s12, s12, s13
	s_cmp_lt_i32 s7, 0
	s_cselect_b32 s12, s79, s12
	v_add3_u32 v125, s12, v110, v111
	v_add_u32_e32 v174, v125, v112
	v_add_u32_e32 v175, v125, v113
	v_add_u32_e32 v252, v125, v114
	v_add_u32_e32 v253, v125, v115
	ds_read_b128 v[158:161], v174
	ds_read_b128 v[162:165], v175
	ds_read_b128 v[166:169], v252
	ds_read_b128 v[170:173], v253
	ds_read_b128 v[240:243], v174 offset:4096
	ds_read_b128 v[244:247], v175 offset:4096
	ds_read_b128 v[248:251], v252 offset:4096
	ds_read_b128 v[104:107], v253 offset:4096
	s_nop 15
	v_cndmask_b32_e32 v0, v124, v126, vcc
	v_sub_f32_e32 v125, v124, v0
	v_exp_f32_e32 v125, v125
	v_mov_b32_e32 v124, v0
	s_nop 0
	v_mul_f32_e32 v123, v123, v125
	v_mul_f32_e32 v34, v34, v125
	v_mul_f32_e32 v35, v35, v125
	v_mul_f32_e32 v36, v36, v125
	v_mul_f32_e32 v37, v37, v125
	v_mul_f32_e32 v38, v38, v125
	v_mul_f32_e32 v39, v39, v125
	v_mul_f32_e32 v40, v40, v125
	v_mul_f32_e32 v41, v41, v125
	v_mul_f32_e32 v42, v42, v125
	v_mul_f32_e32 v43, v43, v125
	v_mul_f32_e32 v44, v44, v125
	v_mul_f32_e32 v45, v45, v125
	v_mul_f32_e32 v46, v46, v125
	v_mul_f32_e32 v47, v47, v125
	v_mul_f32_e32 v48, v48, v125
	v_mul_f32_e32 v49, v49, v125
	v_mul_f32_e32 v50, v50, v125
	v_mul_f32_e32 v51, v51, v125
	v_mul_f32_e32 v52, v52, v125
	v_mul_f32_e32 v53, v53, v125
	v_mul_f32_e32 v54, v54, v125
	v_mul_f32_e32 v55, v55, v125
	v_mul_f32_e32 v56, v56, v125
	v_mul_f32_e32 v57, v57, v125
	v_mul_f32_e32 v58, v58, v125
	v_mul_f32_e32 v59, v59, v125
	v_mul_f32_e32 v60, v60, v125
	v_mul_f32_e32 v61, v61, v125
	v_mul_f32_e32 v62, v62, v125
	v_mul_f32_e32 v63, v63, v125
	v_mul_f32_e32 v64, v64, v125
	v_mul_f32_e32 v65, v65, v125
	v_cndmask_b32_e64 v129, v124, v180, s[16:17]
	v_sub_f32_e32 v0, v66, v129
	v_sub_f32_e32 v126, v67, v129
	v_sub_f32_e32 v127, v68, v129
	v_sub_f32_e32 v128, v69, v129
	v_exp_f32_e32 v66, v0
	v_exp_f32_e32 v67, v126
	v_exp_f32_e32 v68, v127
	v_exp_f32_e32 v69, v128
	v_sub_f32_e32 v0, v70, v129
	v_sub_f32_e32 v126, v71, v129
	v_sub_f32_e32 v127, v72, v129
	v_sub_f32_e32 v128, v73, v129
	v_exp_f32_e32 v70, v0
	v_exp_f32_e32 v71, v126
	v_exp_f32_e32 v72, v127
	v_exp_f32_e32 v73, v128
	v_sub_f32_e32 v0, v74, v129
	v_sub_f32_e32 v126, v75, v129
	v_sub_f32_e32 v127, v76, v129
	v_sub_f32_e32 v128, v77, v129
	v_exp_f32_e32 v74, v0
	v_exp_f32_e32 v75, v126
	v_exp_f32_e32 v76, v127
	v_exp_f32_e32 v77, v128
	v_sub_f32_e32 v0, v78, v129
	v_sub_f32_e32 v126, v79, v129
	v_sub_f32_e32 v127, v80, v129
	v_sub_f32_e32 v128, v81, v129
	v_exp_f32_e32 v78, v0
	v_exp_f32_e32 v79, v126
	v_exp_f32_e32 v80, v127
	v_exp_f32_e32 v81, v128
	s_branch .Lslc_s0done
.Lslc_done:
	v_add3_u32 v0, s78, v117, v118
	v_add3_u32 v0, v0, v119, v120
	v_add_u32_e32 v252, v0, v121
	v_add_u32_e32 v253, v0, v122
	ds_read_b64_tr_b16 v[192:193], v252 offset:8192
	ds_read_b64_tr_b16 v[194:195], v252 offset:9216
	ds_read_b64_tr_b16 v[196:197], v253 offset:8192
	ds_read_b64_tr_b16 v[198:199], v253 offset:9216
	ds_read_b64_tr_b16 v[200:201], v252 offset:10240
	ds_read_b64_tr_b16 v[202:203], v252 offset:11264
	ds_read_b64_tr_b16 v[204:205], v253 offset:10240
	ds_read_b64_tr_b16 v[206:207], v253 offset:11264
	ds_read_b64_tr_b16 v[208:209], v252 offset:12288
	ds_read_b64_tr_b16 v[210:211], v252 offset:13312
	ds_read_b64_tr_b16 v[212:213], v253 offset:12288
	ds_read_b64_tr_b16 v[214:215], v253 offset:13312
	s_waitcnt lgkmcnt(8)
	v_mfma_f32_32x32x16_bf16 v[50:65], v[192:195], v[224:227], v[50:65]
	v_mfma_f32_32x32x16_bf16 v[34:49], v[196:199], v[224:227], v[34:49]
	ds_read_b64_tr_b16 v[216:217], v252 offset:14336
	ds_read_b64_tr_b16 v[218:219], v252 offset:15360
	ds_read_b64_tr_b16 v[220:221], v253 offset:14336
	ds_read_b64_tr_b16 v[222:223], v253 offset:15360
	s_waitcnt lgkmcnt(8)
	v_mfma_f32_32x32x16_bf16 v[50:65], v[200:203], v[228:231], v[50:65]
	v_mfma_f32_32x32x16_bf16 v[34:49], v[204:207], v[228:231], v[34:49]
	s_waitcnt lgkmcnt(4)
	v_mfma_f32_32x32x16_bf16 v[50:65], v[208:211], v[232:235], v[50:65]
	v_mfma_f32_32x32x16_bf16 v[34:49], v[212:215], v[232:235], v[34:49]
	s_waitcnt lgkmcnt(0)
	v_mfma_f32_32x32x16_bf16 v[50:65], v[216:219], v[236:239], v[50:65]
	v_mfma_f32_32x32x16_bf16 v[34:49], v[220:223], v[236:239], v[34:49]
	s_barrier
	s_nop 12
	v_mov_b32_e32 v191, v123
	s_branch .LBB0_1345
